# P1: half of the workgroups (block bit 5) enter 4 us later so epilogue store bursts of the two halves alternate
# baseline (speedup 1.0000x reference)
; __device__ __forceinline__ int hw_lane() { int l = (int)__builtin_amdgcn_mbcnt_hi(~0u, __builtin_amdgcn_mbcnt_lo(~0u, 0u)); asm volatile("" : "+v"(l)); return l; }
; __global__ void __launch_bounds__(NTHR, 2) hybrid_fwd(Args args) {
;     ...
;     for (int rep_ = 0; rep_ < REP_P1; ++rep_) {
;     DECL_PTRS
;     (void)x; (void)mem; (void)out; (void)CC;
;     {
;         const int lane = hw_lane();
;         for (int rb_ = 0; rb_ < REP_P1B; ++rb_)
;         { pg8::Gemm g{XB, W1t, T, 4096, 1024}; pg8::StaticOrder S; S.init(T, 4096, G, blk);
;           epi::InProj E{UB, QF, KF, VF, GT, SSQ0, b_gate};
;           pg8::gemm_phase<epi::InProj, pg8::StaticOrder, PG8_ALIGN, PG8_SP2>(ldsl, g, S, E, wave); }
.LBB0_221:
	s_cmp_eq_u32 s20, 0x100
	s_cbranch_scc0 .Lstg0_done
	s_bitcmp1_b32 s2, 5
	s_cbranch_scc0 .Lstg0_done
	s_sleep 127
